# barrier-poll back-off: s_sleep 1 -> s_sleep 2 in all 34 grid-barrier spin loops, on top of v12
# speedup vs baseline: 1.0035x; 1.0021x over previous
; __global__ void __launch_bounds__(NT, 2) fwd_megakernel(Params p) {
;     ...
;     grid.sync();
.LBB0_252:
	s_sleep 2
	global_load_dword v2, v0, s[2:3] offset:32 sc1
	s_waitcnt vmcnt(0)
	v_and_b32_e32 v2, 0xffff0000, v2
	v_cmp_ne_u32_e32 vcc, v2, v1
	s_or_b64 s[6:7], vcc, s[6:7]
	s_andn2_b64 exec, exec, s[6:7]
	s_cbranch_execnz .LBB0_252

; __device__ __forceinline__ unsigned xb_ld(unsigned* p)              { return __hip_atomic_load(p, __ATOMIC_RELAXED, __HIP_MEMORY_SCOPE_AGENT); }
; __device__ __forceinline__ void xcd_barrier_complete(unsigned* bar, unsigned x, unsigned& nloc, unsigned& nx) {
;     const unsigned G = gridDim.x * gridDim.y * gridDim.z;
;     unsigned sum, cnt, mine, sp = 0u;
;     for (;;) {
;         sum = 0u; cnt = 0u; mine = 0u;
; #pragma unroll
;         for (unsigned j = 0; j < 16; ++j) { const unsigned c = xb_ld(&bar[XB_XCNT(j)]); sum += c; cnt += (c > 0u) ? 1u : 0u; mine = (j == x) ? c : mine; }
;         if (sum == G) break;
;         __builtin_amdgcn_s_sleep(1);
;         if ((++sp & 255u) == 0u) { if (xb_ld(&bar[XB_TMO])) break; if (sp > XB_SPIN_CAP) { atomicAdd(&bar[XB_TMO], 1u); break; } }
;     }
.LBB0_266:
	flat_load_dword v25, v[0:1] offset:1024 sc1
	flat_load_dword v10, v[0:1] offset:1280 sc1
	flat_load_dword v11, v[0:1] offset:1536 sc1
	flat_load_dword v12, v[0:1] offset:1792 sc1
	flat_load_dword v13, v[0:1] offset:2048 sc1
	flat_load_dword v14, v[0:1] offset:2304 sc1
	flat_load_dword v15, v[0:1] offset:2560 sc1
	flat_load_dword v16, v[0:1] offset:2816 sc1
	flat_load_dword v17, v[0:1] offset:3072 sc1
	flat_load_dword v18, v[0:1] offset:3328 sc1
	flat_load_dword v19, v[0:1] offset:3584 sc1
	flat_load_dword v20, v[0:1] offset:3840 sc1
	flat_load_dword v21, v[2:3] sc1
	flat_load_dword v22, v[4:5] sc1
	flat_load_dword v23, v[6:7] sc1
	flat_load_dword v24, v[8:9] sc1
	s_or_b64 s[8:9], s[8:9], exec
	s_or_b64 s[6:7], s[6:7], exec
	s_waitcnt vmcnt(0) lgkmcnt(0)
	v_add_u32_e32 v26, v10, v25
	v_add_u32_e32 v26, v26, v11
	v_add_u32_e32 v26, v26, v12
	v_add_u32_e32 v26, v26, v13
	v_add_u32_e32 v26, v26, v14
	v_add_u32_e32 v26, v26, v15
	v_add_u32_e32 v26, v26, v16
	v_add_u32_e32 v26, v26, v17
	v_add_u32_e32 v26, v26, v18
	v_add_u32_e32 v26, v26, v19
	v_add_u32_e32 v26, v26, v20
	v_add_u32_e32 v26, v26, v21
	v_add_u32_e32 v26, v26, v22
	v_add_u32_e32 v26, v26, v23
	v_add_u32_e32 v26, v26, v24
	v_cmp_ne_u32_e32 vcc, s20, v26
	s_and_saveexec_b64 s[10:11], vcc
	s_cbranch_execz .LBB0_265
	s_and_b32 s14, s21, 0xff
	s_mov_b64 s[12:13], -1
	s_cmp_eq_u32 s14, 0
	s_mov_b64 s[16:17], -1
	s_mov_b64 s[14:15], -1
	s_sleep 2
	s_cbranch_scc1 .LBB0_269
	s_and_saveexec_b64 s[18:19], s[16:17]
	s_cbranch_execz .LBB0_264
	s_branch .LBB0_272

.LBB0_280:
	s_and_b32 s16, s24, 0xff
	s_mov_b64 s[14:15], -1
	s_cmp_lg_u32 s16, 0
	s_mov_b64 s[16:17], -1
	s_sleep 2
	s_cbranch_scc1 .LBB0_284
	v_mov_b64_e32 v[2:3], s[34:35]
	flat_load_dword v0, v[2:3] offset:512 sc1
	s_mov_b64 s[16:17], 0
	s_mov_b64 s[18:19], -1
	s_waitcnt vmcnt(0) lgkmcnt(0)
	v_cmp_eq_u32_e32 vcc, 0, v0
	s_and_saveexec_b64 s[20:21], vcc
	s_cmp_lt_u32 s24, 0x40001
	s_cselect_b64 s[16:17], -1, 0
	s_xor_b64 s[18:19], exec, -1
	s_and_b64 s[16:17], s[16:17], exec
	s_or_b64 exec, exec, s[20:21]

.LBB0_294:
	s_and_b32 s14, s24, 0xff
	s_cmp_lg_u32 s14, 0
	s_mov_b64 s[16:17], -1
	s_sleep 2
	s_cbranch_scc0 .LBB0_296
	s_mov_b64 s[18:19], -1
	s_and_saveexec_b64 s[20:21], s[16:17]
	s_cbranch_execz .LBB0_293
	s_branch .LBB0_299

; __device__ __forceinline__ unsigned xb_ld(unsigned* p)              { return __hip_atomic_load(p, __ATOMIC_RELAXED, __HIP_MEMORY_SCOPE_AGENT); }
; __device__ __forceinline__ void xcd_barrier_complete(unsigned* bar, unsigned x, unsigned& nloc, unsigned& nx) {
;     const unsigned G = gridDim.x * gridDim.y * gridDim.z;
;     unsigned sum, cnt, mine, sp = 0u;
;     for (;;) {
;         sum = 0u; cnt = 0u; mine = 0u;
; #pragma unroll
;         for (unsigned j = 0; j < 16; ++j) { const unsigned c = xb_ld(&bar[XB_XCNT(j)]); sum += c; cnt += (c > 0u) ? 1u : 0u; mine = (j == x) ? c : mine; }
;         if (sum == G) break;
;         __builtin_amdgcn_s_sleep(1);
;         if ((++sp & 255u) == 0u) { if (xb_ld(&bar[XB_TMO])) break; if (sp > XB_SPIN_CAP) { atomicAdd(&bar[XB_TMO], 1u); break; } }
;     }
.LBB0_335:
	v_mov_b64_e32 v[14:15], s[34:35]
	flat_load_dword v12, v[14:15] offset:1024 sc1
	s_waitcnt lgkmcnt(0)
	flat_load_dword v0, v[14:15] offset:1280 sc1
	flat_load_dword v2, v[14:15] offset:1536 sc1
	flat_load_dword v3, v[14:15] offset:1792 sc1
	flat_load_dword v4, v[14:15] offset:2048 sc1
	flat_load_dword v5, v[14:15] offset:2304 sc1
	flat_load_dword v6, v[14:15] offset:2560 sc1
	flat_load_dword v7, v[14:15] offset:2816 sc1
	flat_load_dword v8, v[14:15] offset:3072 sc1
	flat_load_dword v9, v[14:15] offset:3328 sc1
	flat_load_dword v10, v[14:15] offset:3584 sc1
	flat_load_dword v11, v[14:15] offset:3840 sc1
	v_mov_b64_e32 v[14:15], s[0:1]
	flat_load_dword v13, v[14:15] sc1
	v_mov_b64_e32 v[14:15], s[4:5]
	flat_load_dword v14, v[14:15] sc1
	v_mov_b64_e32 v[16:17], s[6:7]
	flat_load_dword v15, v[16:17] sc1
	v_mov_b64_e32 v[16:17], s[8:9]
	flat_load_dword v16, v[16:17] sc1
	v_readlane_b32 s18, v253, 57
	s_or_b64 s[16:17], s[16:17], exec
	s_or_b64 s[14:15], s[14:15], exec
	s_waitcnt vmcnt(0) lgkmcnt(0)
	v_add_u32_e32 v17, v0, v12
	v_add_u32_e32 v17, v17, v2
	v_add_u32_e32 v17, v17, v3
	v_add_u32_e32 v17, v17, v4
	v_add_u32_e32 v17, v17, v5
	v_add_u32_e32 v17, v17, v6
	v_add_u32_e32 v17, v17, v7
	v_add_u32_e32 v17, v17, v8
	v_add_u32_e32 v17, v17, v9
	v_add_u32_e32 v17, v17, v10
	v_add_u32_e32 v17, v17, v11
	v_add_u32_e32 v17, v17, v13
	v_add_u32_e32 v17, v17, v14
	v_add_u32_e32 v17, v17, v15
	v_add_u32_e32 v17, v17, v16
	v_cmp_ne_u32_e32 vcc, s18, v17
	s_and_saveexec_b64 s[18:19], vcc
	s_cbranch_execz .LBB0_334
	s_and_b32 s22, s28, 0xff
	s_mov_b64 s[20:21], -1
	s_cmp_eq_u32 s22, 0
	s_mov_b64 s[24:25], -1
	s_mov_b64 s[22:23], -1
	s_sleep 2
	s_cbranch_scc1 .LBB0_338
	s_and_saveexec_b64 s[26:27], s[24:25]
	s_cbranch_execz .LBB0_333
	s_branch .LBB0_341

.LBB0_349:
	s_and_b32 s16, s22, 0xff
	s_mov_b64 s[14:15], -1
	s_cmp_lg_u32 s16, 0
	s_mov_b64 s[16:17], -1
	s_sleep 2
	s_cbranch_scc1 .LBB0_353
	v_mov_b64_e32 v[4:5], s[34:35]
	flat_load_dword v0, v[4:5] offset:512 sc1
	s_mov_b64 s[16:17], 0
	s_mov_b64 s[18:19], -1
	s_waitcnt vmcnt(0) lgkmcnt(0)
	v_cmp_eq_u32_e32 vcc, 0, v0
	s_and_saveexec_b64 s[20:21], vcc
	s_cmp_lt_u32 s22, 0x40001
	s_cselect_b64 s[16:17], -1, 0
	s_xor_b64 s[18:19], exec, -1
	s_and_b64 s[16:17], s[16:17], exec
	s_or_b64 exec, exec, s[20:21]

.LBB0_363:
	s_and_b32 s18, s26, 0xff
	s_mov_b64 s[16:17], -1
	s_cmp_lg_u32 s18, 0
	s_mov_b64 s[20:21], -1
	s_sleep 2
	s_cbranch_scc0 .LBB0_365
	s_and_saveexec_b64 s[22:23], s[20:21]
	s_cbranch_execz .LBB0_362
	s_branch .LBB0_368

; __device__ __forceinline__ unsigned xb_ld(unsigned* p)              { return __hip_atomic_load(p, __ATOMIC_RELAXED, __HIP_MEMORY_SCOPE_AGENT); }
; __device__ __forceinline__ void xcd_barrier_complete(unsigned* bar, unsigned x, unsigned& nloc, unsigned& nx) {
;     const unsigned G = gridDim.x * gridDim.y * gridDim.z;
;     unsigned sum, cnt, mine, sp = 0u;
;     for (;;) {
;         sum = 0u; cnt = 0u; mine = 0u;
; #pragma unroll
;         for (unsigned j = 0; j < 16; ++j) { const unsigned c = xb_ld(&bar[XB_XCNT(j)]); sum += c; cnt += (c > 0u) ? 1u : 0u; mine = (j == x) ? c : mine; }
;         if (sum == G) break;
;         __builtin_amdgcn_s_sleep(1);
;         if ((++sp & 255u) == 0u) { if (xb_ld(&bar[XB_TMO])) break; if (sp > XB_SPIN_CAP) { atomicAdd(&bar[XB_TMO], 1u); break; } }
;     }
.LBB0_547:
	v_mov_b64_e32 v[12:13], s[38:39]
	flat_load_dword v2, v[12:13] offset:1024 sc1
	s_waitcnt lgkmcnt(0)
	flat_load_dword v0, v[12:13] offset:1280 sc1
	flat_load_dword v3, v[12:13] offset:1536 sc1
	v_readlane_b32 s16, v253, 57
	s_or_b64 s[14:15], s[14:15], exec
	s_or_b64 s[12:13], s[12:13], exec
	s_waitcnt vmcnt(0) lgkmcnt(0)
	v_add_u32_e32 v4, v0, v2
	v_add_u32_e32 v5, v4, v3
	flat_load_dword v4, v[12:13] offset:1792 sc1
	s_waitcnt vmcnt(0) lgkmcnt(0)
	v_add_u32_e32 v6, v5, v4
	flat_load_dword v5, v[12:13] offset:2048 sc1
	s_waitcnt vmcnt(0) lgkmcnt(0)
	v_add_u32_e32 v7, v6, v5
	flat_load_dword v6, v[12:13] offset:2304 sc1
	s_waitcnt vmcnt(0) lgkmcnt(0)
	v_add_u32_e32 v8, v7, v6
	flat_load_dword v7, v[12:13] offset:2560 sc1
	s_waitcnt vmcnt(0) lgkmcnt(0)
	v_add_u32_e32 v9, v8, v7
	flat_load_dword v8, v[12:13] offset:2816 sc1
	s_waitcnt vmcnt(0) lgkmcnt(0)
	v_add_u32_e32 v10, v9, v8
	flat_load_dword v9, v[12:13] offset:3072 sc1
	s_waitcnt vmcnt(0) lgkmcnt(0)
	v_add_u32_e32 v11, v10, v9
	flat_load_dword v10, v[12:13] offset:3328 sc1
	s_waitcnt vmcnt(0) lgkmcnt(0)
	v_add_u32_e32 v14, v11, v10
	flat_load_dword v11, v[12:13] offset:3584 sc1
	s_waitcnt vmcnt(0) lgkmcnt(0)
	v_add_u32_e32 v14, v14, v11
	flat_load_dword v12, v[12:13] offset:3840 sc1
	s_waitcnt vmcnt(0) lgkmcnt(0)
	v_add_u32_e32 v16, v14, v12
	v_mov_b64_e32 v[14:15], s[0:1]
	flat_load_dword v13, v[14:15] sc1
	v_mov_b64_e32 v[14:15], s[2:3]
	flat_load_dword v14, v[14:15] sc1
	s_waitcnt vmcnt(0) lgkmcnt(0)
	v_add_u32_e32 v16, v16, v13
	v_add_u32_e32 v18, v16, v14
	v_mov_b64_e32 v[16:17], s[4:5]
	flat_load_dword v15, v[16:17] sc1
	v_mov_b64_e32 v[16:17], s[6:7]
	flat_load_dword v16, v[16:17] sc1
	s_waitcnt vmcnt(0) lgkmcnt(0)
	v_add_u32_e32 v18, v18, v15
	v_add_u32_e32 v17, v18, v16
	v_cmp_ne_u32_e32 vcc, s16, v17
	s_and_saveexec_b64 s[16:17], vcc
	s_cbranch_execz .LBB0_546
	s_and_b32 s20, s26, 0xff
	s_mov_b64 s[18:19], -1
	s_cmp_eq_u32 s20, 0
	s_mov_b64 s[22:23], -1
	s_mov_b64 s[20:21], -1
	s_sleep 2
	s_cbranch_scc1 .LBB0_550
	s_and_saveexec_b64 s[24:25], s[22:23]
	s_cbranch_execz .LBB0_545
	s_branch .LBB0_553

.LBB0_561:
	s_and_b32 s14, s22, 0xff
	s_mov_b64 s[12:13], -1
	s_cmp_lg_u32 s14, 0
	s_mov_b64 s[14:15], -1
	s_sleep 2
	s_cbranch_scc1 .LBB0_565
	v_mov_b64_e32 v[4:5], s[38:39]
	flat_load_dword v0, v[4:5] offset:512 sc1
	s_mov_b64 s[14:15], 0
	s_mov_b64 s[16:17], -1
	s_waitcnt vmcnt(0) lgkmcnt(0)
	v_cmp_eq_u32_e32 vcc, 0, v0
	s_and_saveexec_b64 s[18:19], vcc
	s_cmp_lt_u32 s22, 0x40001
	s_cselect_b64 s[14:15], -1, 0
	s_xor_b64 s[16:17], exec, -1
	s_and_b64 s[14:15], s[14:15], exec
	s_or_b64 exec, exec, s[18:19]

.LBB0_575:
	s_and_b32 s14, s22, 0xff
	s_mov_b64 s[12:13], -1
	s_cmp_lg_u32 s14, 0
	s_mov_b64 s[16:17], -1
	s_sleep 2
	s_cbranch_scc0 .LBB0_577
	s_and_saveexec_b64 s[18:19], s[16:17]
	s_cbranch_execz .LBB0_574
	s_branch .LBB0_580

.LBB0_610:
	s_and_b32 s14, s20, 0xff
	s_mov_b64 s[12:13], -1
	s_cmp_lg_u32 s14, 0
	s_mov_b64 s[14:15], -1
	s_sleep 2
	s_cbranch_scc1 .LBB0_614
	v_mov_b64_e32 v[4:5], s[38:39]
	flat_load_dword v0, v[4:5] offset:512 sc1
	s_mov_b64 s[14:15], 0
	s_mov_b64 s[16:17], -1
	s_waitcnt vmcnt(0) lgkmcnt(0)
	v_cmp_eq_u32_e32 vcc, 0, v0
	s_and_saveexec_b64 s[18:19], vcc
	s_cmp_lt_u32 s20, 0x40001
	s_cselect_b64 s[14:15], -1, 0
	s_xor_b64 s[16:17], exec, -1
	s_and_b64 s[14:15], s[14:15], exec
	s_or_b64 exec, exec, s[18:19]

.LBB0_624:
	s_and_b32 s16, s24, 0xff
	s_mov_b64 s[14:15], -1
	s_cmp_lg_u32 s16, 0
	s_mov_b64 s[18:19], -1
	s_sleep 2
	s_cbranch_scc0 .LBB0_626
	s_and_saveexec_b64 s[20:21], s[18:19]
	s_cbranch_execz .LBB0_623
	s_branch .LBB0_629

; __device__ __forceinline__ unsigned xb_ld(unsigned* p)              { return __hip_atomic_load(p, __ATOMIC_RELAXED, __HIP_MEMORY_SCOPE_AGENT); }
; __device__ __forceinline__ void xcd_barrier_complete(unsigned* bar, unsigned x, unsigned& nloc, unsigned& nx) {
;     const unsigned G = gridDim.x * gridDim.y * gridDim.z;
;     unsigned sum, cnt, mine, sp = 0u;
;     for (;;) {
;         sum = 0u; cnt = 0u; mine = 0u;
; #pragma unroll
;         for (unsigned j = 0; j < 16; ++j) { const unsigned c = xb_ld(&bar[XB_XCNT(j)]); sum += c; cnt += (c > 0u) ? 1u : 0u; mine = (j == x) ? c : mine; }
;         if (sum == G) break;
;         __builtin_amdgcn_s_sleep(1);
;         if ((++sp & 255u) == 0u) { if (xb_ld(&bar[XB_TMO])) break; if (sp > XB_SPIN_CAP) { atomicAdd(&bar[XB_TMO], 1u); break; } }
;     }
.LBB0_1101:
	v_mov_b64_e32 v[12:13], s[36:37]
	flat_load_dword v2, v[12:13] offset:1024 sc1
	s_waitcnt lgkmcnt(0)
	flat_load_dword v0, v[12:13] offset:1280 sc1
	flat_load_dword v3, v[12:13] offset:1536 sc1
	v_readlane_b32 s16, v253, 57
	s_or_b64 s[14:15], s[14:15], exec
	s_or_b64 s[12:13], s[12:13], exec
	s_waitcnt vmcnt(0) lgkmcnt(0)
	v_add_u32_e32 v4, v0, v2
	v_add_u32_e32 v5, v4, v3
	flat_load_dword v4, v[12:13] offset:1792 sc1
	s_waitcnt vmcnt(0) lgkmcnt(0)
	v_add_u32_e32 v6, v5, v4
	flat_load_dword v5, v[12:13] offset:2048 sc1
	s_waitcnt vmcnt(0) lgkmcnt(0)
	v_add_u32_e32 v7, v6, v5
	flat_load_dword v6, v[12:13] offset:2304 sc1
	s_waitcnt vmcnt(0) lgkmcnt(0)
	v_add_u32_e32 v8, v7, v6
	flat_load_dword v7, v[12:13] offset:2560 sc1
	s_waitcnt vmcnt(0) lgkmcnt(0)
	v_add_u32_e32 v9, v8, v7
	flat_load_dword v8, v[12:13] offset:2816 sc1
	s_waitcnt vmcnt(0) lgkmcnt(0)
	v_add_u32_e32 v10, v9, v8
	flat_load_dword v9, v[12:13] offset:3072 sc1
	s_waitcnt vmcnt(0) lgkmcnt(0)
	v_add_u32_e32 v11, v10, v9
	flat_load_dword v10, v[12:13] offset:3328 sc1
	s_waitcnt vmcnt(0) lgkmcnt(0)
	v_add_u32_e32 v14, v11, v10
	flat_load_dword v11, v[12:13] offset:3584 sc1
	s_waitcnt vmcnt(0) lgkmcnt(0)
	v_add_u32_e32 v14, v14, v11
	flat_load_dword v12, v[12:13] offset:3840 sc1
	s_waitcnt vmcnt(0) lgkmcnt(0)
	v_add_u32_e32 v16, v14, v12
	v_mov_b64_e32 v[14:15], s[0:1]
	flat_load_dword v13, v[14:15] sc1
	v_mov_b64_e32 v[14:15], s[2:3]
	flat_load_dword v14, v[14:15] sc1
	s_waitcnt vmcnt(0) lgkmcnt(0)
	v_add_u32_e32 v16, v16, v13
	v_add_u32_e32 v18, v16, v14
	v_mov_b64_e32 v[16:17], s[4:5]
	flat_load_dword v15, v[16:17] sc1
	v_mov_b64_e32 v[16:17], s[6:7]
	flat_load_dword v16, v[16:17] sc1
	s_waitcnt vmcnt(0) lgkmcnt(0)
	v_add_u32_e32 v18, v18, v15
	v_add_u32_e32 v17, v18, v16
	v_cmp_ne_u32_e32 vcc, s16, v17
	s_and_saveexec_b64 s[16:17], vcc
	s_cbranch_execz .LBB0_1100
	s_and_b32 s20, s26, 0xff
	s_mov_b64 s[18:19], -1
	s_cmp_eq_u32 s20, 0
	s_mov_b64 s[22:23], -1
	s_mov_b64 s[20:21], -1
	s_sleep 2
	s_cbranch_scc1 .LBB0_1104
	s_and_saveexec_b64 s[24:25], s[22:23]
	s_cbranch_execz .LBB0_1099
	s_branch .LBB0_1107

.LBB0_1115:
	s_and_b32 s14, s22, 0xff
	s_mov_b64 s[12:13], -1
	s_cmp_lg_u32 s14, 0
	s_mov_b64 s[14:15], -1
	s_sleep 2
	s_cbranch_scc1 .LBB0_1119
	v_mov_b64_e32 v[4:5], s[36:37]
	flat_load_dword v0, v[4:5] offset:512 sc1
	s_mov_b64 s[14:15], 0
	s_mov_b64 s[16:17], -1
	s_waitcnt vmcnt(0) lgkmcnt(0)
	v_cmp_eq_u32_e32 vcc, 0, v0
	s_and_saveexec_b64 s[18:19], vcc
	s_cmp_lt_u32 s22, 0x40001
	s_cselect_b64 s[14:15], -1, 0
	s_xor_b64 s[16:17], exec, -1
	s_and_b64 s[14:15], s[14:15], exec
	s_or_b64 exec, exec, s[18:19]

.LBB0_1372:
	s_and_b32 s14, s20, 0xff
	s_mov_b64 s[12:13], -1
	s_cmp_lg_u32 s14, 0
	s_mov_b64 s[14:15], -1
	s_sleep 2
	s_cbranch_scc1 .LBB0_1376
	v_mov_b64_e32 v[4:5], s[36:37]
	flat_load_dword v0, v[4:5] offset:512 sc1
	s_mov_b64 s[14:15], 0
	s_mov_b64 s[16:17], -1
	s_waitcnt vmcnt(0) lgkmcnt(0)
	v_cmp_eq_u32_e32 vcc, 0, v0
	s_and_saveexec_b64 s[18:19], vcc
	s_cmp_lt_u32 s20, 0x40001
	s_cselect_b64 s[14:15], -1, 0
	s_xor_b64 s[16:17], exec, -1
	s_and_b64 s[14:15], s[14:15], exec
	s_or_b64 exec, exec, s[18:19]
